# G1: SEC7 and SEC8 gate epilogues share one code body (I-cache reuse) on top of SEC2 LDS transpose and SEC4 load grouping
# speedup vs baseline: 1.0069x; 1.0019x over previous
.LBB0_60:
	s_cmp_lt_i32 s2, 4
	s_mov_b64 s[0:1], -1
	s_cbranch_scc1 .LBB0_148
	s_cmp_lt_i32 s2, 6
	s_cbranch_scc1 .LBB0_75
	s_cmp_lt_i32 s2, 7
	s_cbranch_scc1 .LBB0_71
	s_cmp_lg_u32 s2, 7
	s_cbranch_scc0 .LBB0_67
	s_branch .Lsec78_a

.Lsec78_a:
	s_lshl_b32 s0, s48, 8
	v_add_u32_e32 v134, s0, v241
	v_ashrrev_i32_e32 v135, 31, v134
	v_lshl_add_u64 v[146:147], v[134:135], 2, s[70:71]
	global_load_dword v148, v[146:147], off
	global_load_dword v144, v[146:147], off offset:64
	global_load_dword v140, v[146:147], off offset:128
	global_load_dword v2, v[146:147], off offset:192
	v_or_b32_e32 v132, s74, v178
	v_ashrrev_i32_e32 v133, 31, v132
	v_lshlrev_b64 v[132:133], 1, v[132:133]
	s_mov_b32 s0, 0x9ce6000
	s_cmp_eq_u32 s2, 8
	s_cselect_b32 s0, 0xbd25800, s0
	v_or_b32_e32 v142, 16, v134
	v_ashrrev_i32_e32 v143, 31, v142
	v_lshlrev_b64 v[142:143], 11, v[142:143]
	v_lshl_add_u64 v[142:143], s[94:95], 0, v[142:143]
	v_or_b32_e32 v138, 32, v134
	v_ashrrev_i32_e32 v139, 31, v138
	v_lshlrev_b64 v[138:139], 11, v[138:139]
	v_lshl_add_u64 v[138:139], s[94:95], 0, v[138:139]
	v_or_b32_e32 v136, 48, v134
	v_ashrrev_i32_e32 v137, 31, v136
	v_lshlrev_b64 v[136:137], 11, v[136:137]
	v_lshl_add_u64 v[136:137], s[94:95], 0, v[136:137]
	s_cmp_eq_u32 s48, 64
	s_waitcnt vmcnt(0)
	v_pk_mul_f32 v[146:147], v[130:131], v[148:149] op_sel_hi:[1,0]
	s_nop 0
	v_mul_f32_e32 v146, 0xbfb8aa3b, v146
	v_exp_f32_e32 v146, v146
	v_pk_mul_f32 v[150:151], v[128:129], v[148:149] op_sel_hi:[1,0]
	v_add_f32_e32 v146, 1.0, v146
	v_rcp_f32_e32 v152, v146
	v_mul_f32_e32 v146, 0xbfb8aa3b, v147
	v_exp_f32_e32 v146, v146
	v_mul_f32_e32 v141, 0xbfb8aa3b, v150
	v_mul_f32_e32 v145, 0xbfb8aa3b, v151
	v_exp_f32_e32 v141, v141
	v_add_f32_e32 v146, 1.0, v146
	v_rcp_f32_e32 v153, v146
	v_pk_mul_f32 v[146:147], v[126:127], v[148:149] op_sel_hi:[1,0]
	v_pk_mul_f32 v[148:149], v[124:125], v[148:149] op_sel_hi:[1,0]
	v_mul_f32_e32 v146, 0xbfb8aa3b, v146
	v_exp_f32_e32 v146, v146
	v_mul_f32_e32 v148, 0xbfb8aa3b, v148
	v_mul_f32_e32 v149, 0xbfb8aa3b, v149
	v_exp_f32_e32 v145, v145
	v_add_f32_e32 v146, 1.0, v146
	v_rcp_f32_e32 v154, v146
	v_mul_f32_e32 v146, 0xbfb8aa3b, v147
	v_exp_f32_e32 v148, v148
	v_exp_f32_e32 v149, v149
	v_exp_f32_e32 v146, v146
	v_add_f32_e32 v141, 1.0, v141
	v_add_f32_e32 v145, 1.0, v145
	v_add_f32_e32 v148, 1.0, v148
	v_add_f32_e32 v149, 1.0, v149
	v_add_f32_e32 v146, 1.0, v146
	v_rcp_f32_e32 v141, v141
	v_rcp_f32_e32 v145, v145
	v_rcp_f32_e32 v148, v148
	v_rcp_f32_e32 v149, v149
	v_rcp_f32_e32 v155, v146
	v_lshlrev_b64 v[146:147], 11, v[134:135]
	v_lshl_add_u64 v[146:147], s[94:95], 0, v[146:147]
	v_lshl_add_u64 v[150:151], v[146:147], 0, v[132:133]
	v_add_co_u32_e32 v150, vcc, s0, v150
	v_cvt_pk_bf16_f32 v146, v141, v145
	v_cvt_pk_bf16_f32 v147, v152, v153
	v_cvt_pk_bf16_f32 v148, v148, v149
	v_cvt_pk_bf16_f32 v149, v154, v155
	v_addc_co_u32_e32 v151, vcc, 0, v151, vcc
	global_store_dwordx4 v[150:151], v[146:149], off offset:512
	s_nop 1
	v_pk_mul_f32 v[146:147], v[122:123], v[144:145] op_sel_hi:[1,0]
	v_pk_mul_f32 v[148:149], v[120:121], v[144:145] op_sel_hi:[1,0]
	v_mul_f32_e32 v145, 0xbfb8aa3b, v146
	v_exp_f32_e32 v145, v145
	v_mul_f32_e32 v135, 0xbfb8aa3b, v148
	v_mul_f32_e32 v141, 0xbfb8aa3b, v149
	v_exp_f32_e32 v135, v135
	v_add_f32_e32 v145, 1.0, v145
	v_rcp_f32_e32 v148, v145
	v_mul_f32_e32 v145, 0xbfb8aa3b, v147
	v_exp_f32_e32 v145, v145
	v_exp_f32_e32 v141, v141
	v_add_f32_e32 v135, 1.0, v135
	v_rcp_f32_e32 v135, v135
	v_add_f32_e32 v145, 1.0, v145
	v_pk_mul_f32 v[146:147], v[118:119], v[144:145] op_sel_hi:[1,0]
	v_rcp_f32_e32 v149, v145
	v_mul_f32_e32 v146, 0xbfb8aa3b, v146
	v_exp_f32_e32 v146, v146
	v_pk_mul_f32 v[144:145], v[116:117], v[144:145] op_sel_hi:[1,0]
	v_add_f32_e32 v141, 1.0, v141
	v_mul_f32_e32 v144, 0xbfb8aa3b, v144
	v_add_f32_e32 v146, 1.0, v146
	v_mul_f32_e32 v145, 0xbfb8aa3b, v145
	v_rcp_f32_e32 v150, v146
	v_mul_f32_e32 v146, 0xbfb8aa3b, v147
	v_exp_f32_e32 v144, v144
	v_exp_f32_e32 v145, v145
	v_exp_f32_e32 v146, v146
	v_rcp_f32_e32 v141, v141
	v_add_f32_e32 v144, 1.0, v144
	v_add_f32_e32 v145, 1.0, v145
	v_add_f32_e32 v146, 1.0, v146
	v_rcp_f32_e32 v144, v144
	v_rcp_f32_e32 v145, v145
	v_rcp_f32_e32 v151, v146
	v_lshl_add_u64 v[146:147], v[142:143], 0, v[132:133]
	v_add_co_u32_e32 v146, vcc, s0, v146
	v_cvt_pk_bf16_f32 v142, v135, v141
	v_cvt_pk_bf16_f32 v143, v148, v149
	v_cvt_pk_bf16_f32 v144, v144, v145
	v_cvt_pk_bf16_f32 v145, v150, v151
	v_addc_co_u32_e32 v147, vcc, 0, v147, vcc
	global_store_dwordx4 v[146:147], v[142:145], off offset:512
	s_nop 1
	v_pk_mul_f32 v[144:145], v[112:113], v[140:141] op_sel_hi:[1,0]
	v_pk_mul_f32 v[142:143], v[114:115], v[140:141] op_sel_hi:[1,0]
	v_mul_f32_e32 v141, 0xbfb8aa3b, v145
	v_exp_f32_e32 v141, v141
	v_mul_f32_e32 v135, 0xbfb8aa3b, v144
	v_exp_f32_e32 v135, v135
	v_add_f32_e32 v141, 1.0, v141
	v_rcp_f32_e32 v144, v141
	v_mul_f32_e32 v141, 0xbfb8aa3b, v142
	v_exp_f32_e32 v141, v141
	v_add_f32_e32 v135, 1.0, v135
	v_rcp_f32_e32 v135, v135
	v_add_f32_e32 v141, 1.0, v141
	v_rcp_f32_e32 v145, v141
	v_mul_f32_e32 v141, 0xbfb8aa3b, v143
	v_exp_f32_e32 v141, v141
	s_nop 0
	v_add_f32_e32 v141, 1.0, v141
	v_pk_mul_f32 v[142:143], v[110:111], v[140:141] op_sel_hi:[1,0]
	v_rcp_f32_e32 v146, v141
	v_mul_f32_e32 v142, 0xbfb8aa3b, v142
	v_exp_f32_e32 v142, v142
	v_pk_mul_f32 v[140:141], v[108:109], v[140:141] op_sel_hi:[1,0]
	v_add_f32_e32 v142, 1.0, v142
	v_mul_f32_e32 v140, 0xbfb8aa3b, v140
	v_mul_f32_e32 v141, 0xbfb8aa3b, v141
	v_rcp_f32_e32 v147, v142
	v_mul_f32_e32 v142, 0xbfb8aa3b, v143
	v_exp_f32_e32 v140, v140
	v_exp_f32_e32 v141, v141
	v_exp_f32_e32 v142, v142
	v_add_f32_e32 v140, 1.0, v140
	v_add_f32_e32 v141, 1.0, v141
	v_add_f32_e32 v142, 1.0, v142
	v_rcp_f32_e32 v140, v140
	v_rcp_f32_e32 v141, v141
	v_rcp_f32_e32 v148, v142
	v_lshl_add_u64 v[142:143], v[138:139], 0, v[132:133]
	v_add_co_u32_e32 v142, vcc, s0, v142
	v_cvt_pk_bf16_f32 v138, v135, v144
	v_cvt_pk_bf16_f32 v139, v145, v146
	v_cvt_pk_bf16_f32 v140, v140, v141
	v_cvt_pk_bf16_f32 v141, v147, v148
	v_addc_co_u32_e32 v143, vcc, 0, v143, vcc
	global_store_dwordx4 v[142:143], v[138:141], off offset:512
	s_nop 1
	v_pk_mul_f32 v[138:139], v[106:107], v[2:3] op_sel_hi:[1,0]
	v_pk_mul_f32 v[140:141], v[104:105], v[2:3] op_sel_hi:[1,0]
	v_mul_f32_e32 v138, 0xbfb8aa3b, v138
	v_exp_f32_e32 v138, v138
	v_mul_f32_e32 v135, 0xbfb8aa3b, v140
	v_mul_f32_e32 v140, 0xbfb8aa3b, v141
	v_exp_f32_e32 v140, v140
	v_add_f32_e32 v138, 1.0, v138
	v_rcp_f32_e32 v143, v138
	v_mul_f32_e32 v138, 0xbfb8aa3b, v139
	v_exp_f32_e32 v138, v138
	v_add_f32_e32 v140, 1.0, v140
	v_rcp_f32_e32 v142, v140
	v_pk_mul_f32 v[140:141], v[100:101], v[2:3] op_sel_hi:[1,0]
	v_add_f32_e32 v138, 1.0, v138
	v_rcp_f32_e32 v144, v138
	v_pk_mul_f32 v[138:139], v[102:103], v[2:3] op_sel_hi:[1,0]
	v_mul_f32_e32 v2, 0xbfb8aa3b, v140
	v_mul_f32_e32 v138, 0xbfb8aa3b, v138
	v_exp_f32_e32 v138, v138
	v_mul_f32_e32 v140, 0xbfb8aa3b, v141
	v_exp_f32_e32 v135, v135
	v_exp_f32_e32 v2, v2
	v_add_f32_e32 v138, 1.0, v138
	v_rcp_f32_e32 v146, v138
	v_mul_f32_e32 v138, 0xbfb8aa3b, v139
	v_exp_f32_e32 v140, v140
	v_exp_f32_e32 v138, v138
	v_add_f32_e32 v135, 1.0, v135
	v_add_f32_e32 v2, 1.0, v2
	v_add_f32_e32 v140, 1.0, v140
	v_add_f32_e32 v138, 1.0, v138
	v_rcp_f32_e32 v135, v135
	v_rcp_f32_e32 v2, v2
	v_rcp_f32_e32 v145, v140
	v_rcp_f32_e32 v139, v138
	v_lshl_add_u64 v[140:141], v[136:137], 0, v[132:133]
	v_add_co_u32_e32 v140, vcc, s0, v140
	v_cvt_pk_bf16_f32 v136, v135, v142
	v_cvt_pk_bf16_f32 v137, v143, v144
	v_cvt_pk_bf16_f32 v138, v2, v145
	v_cvt_pk_bf16_f32 v139, v146, v139
	v_addc_co_u32_e32 v141, vcc, 0, v141, vcc
	global_store_dwordx4 v[140:141], v[136:139], off offset:512
	s_cbranch_scc1 .LBB0_70
	v_add_u32_e32 v144, 0x80, v134
	v_ashrrev_i32_e32 v145, 31, v144
	v_lshl_add_u64 v[146:147], v[144:145], 2, s[70:71]
	global_load_dword v148, v[146:147], off
	global_load_dword v142, v[146:147], off offset:64
	global_load_dword v138, v[146:147], off offset:128
	global_load_dword v2, v[146:147], off offset:192
	v_lshlrev_b64 v[144:145], 11, v[144:145]
	v_lshl_add_u64 v[144:145], s[94:95], 0, v[144:145]
	v_add_u32_e32 v140, 0x90, v134
	v_ashrrev_i32_e32 v141, 31, v140
	v_lshlrev_b64 v[140:141], 11, v[140:141]
	v_lshl_add_u64 v[140:141], s[94:95], 0, v[140:141]
	v_add_u32_e32 v136, 0xa0, v134
	v_ashrrev_i32_e32 v137, 31, v136
	v_lshlrev_b64 v[136:137], 11, v[136:137]
	v_lshl_add_u64 v[136:137], s[94:95], 0, v[136:137]
	v_add_u32_e32 v134, 0xb0, v134
	v_ashrrev_i32_e32 v135, 31, v134
	v_lshlrev_b64 v[134:135], 11, v[134:135]
	v_lshl_add_u64 v[134:135], s[94:95], 0, v[134:135]
	s_waitcnt vmcnt(0)
	v_pk_mul_f32 v[146:147], v[98:99], v[148:149] op_sel_hi:[1,0]
	s_nop 0
	v_mul_f32_e32 v146, 0xbfb8aa3b, v146
	v_exp_f32_e32 v146, v146
	v_pk_mul_f32 v[150:151], v[96:97], v[148:149] op_sel_hi:[1,0]
	v_add_f32_e32 v146, 1.0, v146
	v_mul_f32_e32 v139, 0xbfb8aa3b, v150
	v_rcp_f32_e32 v150, v146
	v_mul_f32_e32 v146, 0xbfb8aa3b, v147
	v_exp_f32_e32 v146, v146
	v_mul_f32_e32 v143, 0xbfb8aa3b, v151
	v_exp_f32_e32 v139, v139
	v_exp_f32_e32 v143, v143
	v_add_f32_e32 v146, 1.0, v146
	v_rcp_f32_e32 v151, v146
	v_pk_mul_f32 v[146:147], v[94:95], v[148:149] op_sel_hi:[1,0]
	v_pk_mul_f32 v[148:149], v[92:93], v[148:149] op_sel_hi:[1,0]
	v_mul_f32_e32 v146, 0xbfb8aa3b, v146
	v_mul_f32_e32 v148, 0xbfb8aa3b, v148
	v_exp_f32_e32 v148, v148
	v_exp_f32_e32 v146, v146
	v_add_f32_e32 v139, 1.0, v139
	v_add_f32_e32 v143, 1.0, v143
	v_add_f32_e32 v148, 1.0, v148
	v_add_f32_e32 v146, 1.0, v146
	v_rcp_f32_e32 v152, v148
	v_mul_f32_e32 v148, 0xbfb8aa3b, v149
	v_rcp_f32_e32 v154, v146
	v_mul_f32_e32 v146, 0xbfb8aa3b, v147
	v_exp_f32_e32 v148, v148
	v_exp_f32_e32 v146, v146
	v_rcp_f32_e32 v139, v139
	v_rcp_f32_e32 v143, v143
	v_add_f32_e32 v148, 1.0, v148
	v_add_f32_e32 v146, 1.0, v146
	v_rcp_f32_e32 v153, v148
	v_rcp_f32_e32 v147, v146
	v_lshl_add_u64 v[148:149], v[144:145], 0, v[132:133]
	v_add_co_u32_e32 v148, vcc, s0, v148
	v_cvt_pk_bf16_f32 v144, v139, v143
	v_cvt_pk_bf16_f32 v145, v150, v151
	v_cvt_pk_bf16_f32 v146, v152, v153
	v_cvt_pk_bf16_f32 v147, v154, v147
	v_addc_co_u32_e32 v149, vcc, 0, v149, vcc
	global_store_dwordx4 v[148:149], v[144:147], off offset:512
	s_nop 1
	v_pk_mul_f32 v[146:147], v[88:89], v[142:143] op_sel_hi:[1,0]
	v_pk_mul_f32 v[144:145], v[90:91], v[142:143] op_sel_hi:[1,0]
	v_mul_f32_e32 v143, 0xbfb8aa3b, v147
	v_exp_f32_e32 v143, v143
	v_mul_f32_e32 v139, 0xbfb8aa3b, v146
	v_exp_f32_e32 v139, v139
	v_add_f32_e32 v143, 1.0, v143
	v_rcp_f32_e32 v146, v143
	v_mul_f32_e32 v143, 0xbfb8aa3b, v144
	v_exp_f32_e32 v143, v143
	v_add_f32_e32 v139, 1.0, v139
	v_rcp_f32_e32 v139, v139
	v_add_f32_e32 v143, 1.0, v143
	v_rcp_f32_e32 v147, v143
	v_mul_f32_e32 v143, 0xbfb8aa3b, v145
	v_exp_f32_e32 v143, v143
	s_nop 0
	v_add_f32_e32 v143, 1.0, v143
	v_pk_mul_f32 v[144:145], v[86:87], v[142:143] op_sel_hi:[1,0]
	v_rcp_f32_e32 v148, v143
	v_mul_f32_e32 v144, 0xbfb8aa3b, v144
	v_exp_f32_e32 v144, v144
	v_pk_mul_f32 v[142:143], v[84:85], v[142:143] op_sel_hi:[1,0]
	v_add_f32_e32 v144, 1.0, v144
	v_mul_f32_e32 v142, 0xbfb8aa3b, v142
	v_mul_f32_e32 v143, 0xbfb8aa3b, v143
	v_rcp_f32_e32 v149, v144
	v_mul_f32_e32 v144, 0xbfb8aa3b, v145
	v_exp_f32_e32 v142, v142
	v_exp_f32_e32 v143, v143
	v_exp_f32_e32 v144, v144
	v_add_f32_e32 v142, 1.0, v142
	v_add_f32_e32 v143, 1.0, v143
	v_add_f32_e32 v144, 1.0, v144
	v_rcp_f32_e32 v142, v142
	v_rcp_f32_e32 v143, v143
	v_rcp_f32_e32 v150, v144
	v_lshl_add_u64 v[144:145], v[140:141], 0, v[132:133]
	v_add_co_u32_e32 v144, vcc, s0, v144
	v_cvt_pk_bf16_f32 v140, v139, v146
	v_cvt_pk_bf16_f32 v141, v147, v148
	v_cvt_pk_bf16_f32 v142, v142, v143
	v_cvt_pk_bf16_f32 v143, v149, v150
	v_addc_co_u32_e32 v145, vcc, 0, v145, vcc
	global_store_dwordx4 v[144:145], v[140:143], off offset:512
	s_nop 1
	v_pk_mul_f32 v[142:143], v[80:81], v[138:139] op_sel_hi:[1,0]
	v_pk_mul_f32 v[140:141], v[82:83], v[138:139] op_sel_hi:[1,0]
	v_mul_f32_e32 v139, 0xbfb8aa3b, v142
	v_exp_f32_e32 v139, v139
	s_nop 0
	v_add_f32_e32 v139, 1.0, v139
	v_rcp_f32_e32 v142, v139
	v_mul_f32_e32 v139, 0xbfb8aa3b, v143
	v_exp_f32_e32 v139, v139
	s_nop 0
	v_add_f32_e32 v139, 1.0, v139
	v_rcp_f32_e32 v143, v139
	v_mul_f32_e32 v139, 0xbfb8aa3b, v140
	v_exp_f32_e32 v139, v139
	s_nop 0
	v_add_f32_e32 v139, 1.0, v139
	v_rcp_f32_e32 v144, v139
	v_mul_f32_e32 v139, 0xbfb8aa3b, v141
	v_exp_f32_e32 v139, v139
	s_nop 0
	v_add_f32_e32 v139, 1.0, v139
	v_pk_mul_f32 v[140:141], v[78:79], v[138:139] op_sel_hi:[1,0]
	v_rcp_f32_e32 v145, v139
	v_mul_f32_e32 v140, 0xbfb8aa3b, v140
	v_exp_f32_e32 v140, v140
	v_pk_mul_f32 v[138:139], v[76:77], v[138:139] op_sel_hi:[1,0]
	v_add_f32_e32 v140, 1.0, v140
	v_mul_f32_e32 v138, 0xbfb8aa3b, v138
	v_mul_f32_e32 v139, 0xbfb8aa3b, v139
	v_rcp_f32_e32 v146, v140
	v_mul_f32_e32 v140, 0xbfb8aa3b, v141
	v_exp_f32_e32 v138, v138
	v_exp_f32_e32 v139, v139
	v_exp_f32_e32 v140, v140
	v_add_f32_e32 v138, 1.0, v138
	v_add_f32_e32 v139, 1.0, v139
	v_add_f32_e32 v140, 1.0, v140
	v_rcp_f32_e32 v138, v138
	v_rcp_f32_e32 v139, v139
	v_rcp_f32_e32 v147, v140
	v_lshl_add_u64 v[140:141], v[136:137], 0, v[132:133]
	v_add_co_u32_e32 v140, vcc, s0, v140
	v_cvt_pk_bf16_f32 v136, v142, v143
	v_cvt_pk_bf16_f32 v137, v144, v145
	v_cvt_pk_bf16_f32 v138, v138, v139
	v_cvt_pk_bf16_f32 v139, v146, v147
	v_addc_co_u32_e32 v141, vcc, 0, v141, vcc
	global_store_dwordx4 v[140:141], v[136:139], off offset:512
	s_nop 1
	v_pk_mul_f32 v[136:137], v[74:75], v[2:3] op_sel_hi:[1,0]
	v_pk_mul_f32 v[138:139], v[72:73], v[2:3] op_sel_hi:[1,0]
	v_mul_f32_e32 v136, 0xbfb8aa3b, v136
	v_exp_f32_e32 v136, v136
	v_mul_f32_e32 v138, 0xbfb8aa3b, v138
	v_exp_f32_e32 v138, v138
	v_add_f32_e32 v136, 1.0, v136
	v_rcp_f32_e32 v142, v136
	v_mul_f32_e32 v136, 0xbfb8aa3b, v137
	v_exp_f32_e32 v136, v136
	v_add_f32_e32 v138, 1.0, v138
	v_rcp_f32_e32 v140, v138
	v_mul_f32_e32 v138, 0xbfb8aa3b, v139
	v_add_f32_e32 v136, 1.0, v136
	v_rcp_f32_e32 v143, v136
	v_pk_mul_f32 v[136:137], v[70:71], v[2:3] op_sel_hi:[1,0]
	v_exp_f32_e32 v138, v138
	v_mul_f32_e32 v136, 0xbfb8aa3b, v136
	v_exp_f32_e32 v136, v136
	v_add_f32_e32 v138, 1.0, v138
	v_rcp_f32_e32 v141, v138
	v_pk_mul_f32 v[138:139], v[68:69], v[2:3] op_sel_hi:[1,0]
	v_add_f32_e32 v136, 1.0, v136
	v_mul_f32_e32 v2, 0xbfb8aa3b, v138
	v_mul_f32_e32 v138, 0xbfb8aa3b, v139
	v_rcp_f32_e32 v139, v136
	v_mul_f32_e32 v136, 0xbfb8aa3b, v137
	v_exp_f32_e32 v2, v2
	v_exp_f32_e32 v138, v138
	v_exp_f32_e32 v136, v136
	v_add_f32_e32 v2, 1.0, v2
	v_add_f32_e32 v138, 1.0, v138
	v_add_f32_e32 v136, 1.0, v136
	v_rcp_f32_e32 v2, v2
	v_rcp_f32_e32 v138, v138
	v_rcp_f32_e32 v144, v136
	v_lshl_add_u64 v[136:137], v[134:135], 0, v[132:133]
	v_add_co_u32_e32 v136, vcc, s0, v136
	v_cvt_pk_bf16_f32 v132, v140, v141
	v_cvt_pk_bf16_f32 v133, v142, v143
	v_cvt_pk_bf16_f32 v134, v2, v138
	v_cvt_pk_bf16_f32 v135, v139, v144
	v_addc_co_u32_e32 v137, vcc, 0, v137, vcc
	global_store_dwordx4 v[136:137], v[132:135], off offset:512

.Lsec78_b:
	s_lshl_b32 s2, s48, 8
	v_add_u32_e32 v70, s2, v241
	v_ashrrev_i32_e32 v71, 31, v70
	v_lshl_add_u64 v[68:69], v[70:71], 2, s[70:71]
	global_load_dword v82, v[68:69], off
	global_load_dword v80, v[68:69], off offset:64
	global_load_dword v76, v[68:69], off offset:128
	global_load_dword v2, v[68:69], off offset:192
	s_ashr_i32 s75, s74, 31
	s_mov_b32 s2, 0x9ce6000
	s_cmp_eq_u32 s17, 8
	s_cselect_b32 s2, 0xbd25800, s2
	v_or_b32_e32 v78, 16, v70
	v_ashrrev_i32_e32 v79, 31, v78
	v_lshlrev_b64 v[78:79], 11, v[78:79]
	v_lshl_add_u64 v[78:79], s[94:95], 0, v[78:79]
	v_or_b32_e32 v74, 32, v70
	v_ashrrev_i32_e32 v75, 31, v74
	v_lshlrev_b64 v[74:75], 11, v[74:75]
	v_lshl_add_u64 v[74:75], s[94:95], 0, v[74:75]
	v_or_b32_e32 v72, 48, v70
	v_ashrrev_i32_e32 v73, 31, v72
	v_lshlrev_b64 v[72:73], 11, v[72:73]
	v_lshl_add_u64 v[72:73], s[94:95], 0, v[72:73]
	s_cmp_eq_u32 s48, 64
	s_waitcnt vmcnt(0)
	v_pk_mul_f32 v[68:69], v[66:67], v[82:83] op_sel_hi:[1,0]
	s_nop 0
	v_mul_f32_e32 v68, 0xbfb8aa3b, v68
	v_exp_f32_e32 v68, v68
	v_pk_mul_f32 v[84:85], v[64:65], v[82:83] op_sel_hi:[1,0]
	v_add_f32_e32 v68, 1.0, v68
	v_mul_f32_e32 v77, 0xbfb8aa3b, v84
	v_rcp_f32_e32 v84, v68
	v_mul_f32_e32 v68, 0xbfb8aa3b, v69
	v_exp_f32_e32 v68, v68
	v_mul_f32_e32 v81, 0xbfb8aa3b, v85
	v_exp_f32_e32 v77, v77
	v_exp_f32_e32 v81, v81
	v_add_f32_e32 v68, 1.0, v68
	v_rcp_f32_e32 v85, v68
	v_pk_mul_f32 v[68:69], v[62:63], v[82:83] op_sel_hi:[1,0]
	v_pk_mul_f32 v[82:83], v[60:61], v[82:83] op_sel_hi:[1,0]
	v_mul_f32_e32 v68, 0xbfb8aa3b, v68
	v_mul_f32_e32 v82, 0xbfb8aa3b, v82
	v_exp_f32_e32 v68, v68
	v_exp_f32_e32 v82, v82
	v_add_f32_e32 v77, 1.0, v77
	v_add_f32_e32 v81, 1.0, v81
	v_add_f32_e32 v68, 1.0, v68
	v_add_f32_e32 v82, 1.0, v82
	v_rcp_f32_e32 v90, v68
	v_mul_f32_e32 v68, 0xbfb8aa3b, v69
	v_rcp_f32_e32 v88, v82
	v_mul_f32_e32 v82, 0xbfb8aa3b, v83
	v_exp_f32_e32 v68, v68
	v_exp_f32_e32 v82, v82
	v_rcp_f32_e32 v77, v77
	v_rcp_f32_e32 v81, v81
	v_add_f32_e32 v68, 1.0, v68
	v_add_f32_e32 v82, 1.0, v82
	v_rcp_f32_e32 v91, v68
	v_lshlrev_b64 v[68:69], 11, v[70:71]
	v_rcp_f32_e32 v89, v82
	v_lshl_add_u64 v[82:83], s[94:95], 0, v[68:69]
	v_lshl_add_u64 v[68:69], s[74:75], 0, v[178:179]
	v_lshlrev_b64 v[68:69], 1, v[68:69]
	v_lshl_add_u64 v[86:87], v[82:83], 0, v[68:69]
	v_add_co_u32_e32 v86, vcc, s2, v86
	v_cvt_pk_bf16_f32 v82, v77, v81
	v_cvt_pk_bf16_f32 v83, v84, v85
	v_cvt_pk_bf16_f32 v84, v88, v89
	v_cvt_pk_bf16_f32 v85, v90, v91
	v_addc_co_u32_e32 v87, vcc, 0, v87, vcc
	global_store_dwordx4 v[86:87], v[82:85], off offset:768
	s_nop 1
	v_pk_mul_f32 v[82:83], v[58:59], v[80:81] op_sel_hi:[1,0]
	v_pk_mul_f32 v[84:85], v[56:57], v[80:81] op_sel_hi:[1,0]
	v_mul_f32_e32 v81, 0xbfb8aa3b, v82
	v_exp_f32_e32 v81, v81
	v_mul_f32_e32 v71, 0xbfb8aa3b, v84
	v_mul_f32_e32 v77, 0xbfb8aa3b, v85
	v_exp_f32_e32 v71, v71
	v_add_f32_e32 v81, 1.0, v81
	v_rcp_f32_e32 v84, v81
	v_mul_f32_e32 v81, 0xbfb8aa3b, v83
	v_exp_f32_e32 v81, v81
	v_exp_f32_e32 v77, v77
	v_add_f32_e32 v71, 1.0, v71
	v_rcp_f32_e32 v71, v71
	v_add_f32_e32 v81, 1.0, v81
	v_pk_mul_f32 v[82:83], v[54:55], v[80:81] op_sel_hi:[1,0]
	v_rcp_f32_e32 v85, v81
	v_mul_f32_e32 v82, 0xbfb8aa3b, v82
	v_exp_f32_e32 v82, v82
	v_pk_mul_f32 v[80:81], v[52:53], v[80:81] op_sel_hi:[1,0]
	v_add_f32_e32 v77, 1.0, v77
	v_mul_f32_e32 v80, 0xbfb8aa3b, v80
	v_add_f32_e32 v82, 1.0, v82
	v_mul_f32_e32 v81, 0xbfb8aa3b, v81
	v_rcp_f32_e32 v86, v82
	v_mul_f32_e32 v82, 0xbfb8aa3b, v83
	v_exp_f32_e32 v80, v80
	v_exp_f32_e32 v81, v81
	v_exp_f32_e32 v82, v82
	v_rcp_f32_e32 v77, v77
	v_add_f32_e32 v80, 1.0, v80
	v_add_f32_e32 v81, 1.0, v81
	v_add_f32_e32 v82, 1.0, v82
	v_rcp_f32_e32 v80, v80
	v_rcp_f32_e32 v81, v81
	v_rcp_f32_e32 v87, v82
	v_lshl_add_u64 v[82:83], v[78:79], 0, v[68:69]
	v_add_co_u32_e32 v82, vcc, s2, v82
	v_cvt_pk_bf16_f32 v78, v71, v77
	v_cvt_pk_bf16_f32 v79, v84, v85
	v_cvt_pk_bf16_f32 v80, v80, v81
	v_cvt_pk_bf16_f32 v81, v86, v87
	v_addc_co_u32_e32 v83, vcc, 0, v83, vcc
	global_store_dwordx4 v[82:83], v[78:81], off offset:768
	s_nop 1
	v_pk_mul_f32 v[80:81], v[48:49], v[76:77] op_sel_hi:[1,0]
	v_pk_mul_f32 v[78:79], v[50:51], v[76:77] op_sel_hi:[1,0]
	v_mul_f32_e32 v77, 0xbfb8aa3b, v81
	v_exp_f32_e32 v77, v77
	v_mul_f32_e32 v71, 0xbfb8aa3b, v80
	v_exp_f32_e32 v71, v71
	v_add_f32_e32 v77, 1.0, v77
	v_rcp_f32_e32 v80, v77
	v_mul_f32_e32 v77, 0xbfb8aa3b, v78
	v_exp_f32_e32 v77, v77
	v_add_f32_e32 v71, 1.0, v71
	v_rcp_f32_e32 v71, v71
	v_add_f32_e32 v77, 1.0, v77
	v_rcp_f32_e32 v81, v77
	v_mul_f32_e32 v77, 0xbfb8aa3b, v79
	v_exp_f32_e32 v77, v77
	s_nop 0
	v_add_f32_e32 v77, 1.0, v77
	v_pk_mul_f32 v[78:79], v[46:47], v[76:77] op_sel_hi:[1,0]
	v_rcp_f32_e32 v82, v77
	v_mul_f32_e32 v78, 0xbfb8aa3b, v78
	v_exp_f32_e32 v78, v78
	v_pk_mul_f32 v[76:77], v[44:45], v[76:77] op_sel_hi:[1,0]
	v_add_f32_e32 v78, 1.0, v78
	v_mul_f32_e32 v76, 0xbfb8aa3b, v76
	v_mul_f32_e32 v77, 0xbfb8aa3b, v77
	v_rcp_f32_e32 v83, v78
	v_mul_f32_e32 v78, 0xbfb8aa3b, v79
	v_exp_f32_e32 v76, v76
	v_exp_f32_e32 v77, v77
	v_exp_f32_e32 v78, v78
	v_add_f32_e32 v76, 1.0, v76
	v_add_f32_e32 v77, 1.0, v77
	v_add_f32_e32 v78, 1.0, v78
	v_rcp_f32_e32 v76, v76
	v_rcp_f32_e32 v77, v77
	v_rcp_f32_e32 v84, v78
	v_lshl_add_u64 v[78:79], v[74:75], 0, v[68:69]
	v_add_co_u32_e32 v78, vcc, s2, v78
	v_cvt_pk_bf16_f32 v74, v71, v80
	v_cvt_pk_bf16_f32 v75, v81, v82
	v_cvt_pk_bf16_f32 v76, v76, v77
	v_cvt_pk_bf16_f32 v77, v83, v84
	v_addc_co_u32_e32 v79, vcc, 0, v79, vcc
	global_store_dwordx4 v[78:79], v[74:77], off offset:768
	s_nop 1
	v_pk_mul_f32 v[74:75], v[42:43], v[2:3] op_sel_hi:[1,0]
	v_pk_mul_f32 v[76:77], v[40:41], v[2:3] op_sel_hi:[1,0]
	v_mul_f32_e32 v74, 0xbfb8aa3b, v74
	v_exp_f32_e32 v74, v74
	v_mul_f32_e32 v71, 0xbfb8aa3b, v76
	v_mul_f32_e32 v76, 0xbfb8aa3b, v77
	v_exp_f32_e32 v76, v76
	v_add_f32_e32 v74, 1.0, v74
	v_rcp_f32_e32 v79, v74
	v_mul_f32_e32 v74, 0xbfb8aa3b, v75
	v_exp_f32_e32 v74, v74
	v_add_f32_e32 v76, 1.0, v76
	v_rcp_f32_e32 v78, v76
	v_pk_mul_f32 v[76:77], v[36:37], v[2:3] op_sel_hi:[1,0]
	v_add_f32_e32 v74, 1.0, v74
	v_rcp_f32_e32 v80, v74
	v_pk_mul_f32 v[74:75], v[38:39], v[2:3] op_sel_hi:[1,0]
	v_mul_f32_e32 v2, 0xbfb8aa3b, v76
	v_mul_f32_e32 v74, 0xbfb8aa3b, v74
	v_exp_f32_e32 v74, v74
	v_mul_f32_e32 v76, 0xbfb8aa3b, v77
	v_exp_f32_e32 v71, v71
	v_exp_f32_e32 v2, v2
	v_add_f32_e32 v74, 1.0, v74
	v_rcp_f32_e32 v82, v74
	v_mul_f32_e32 v74, 0xbfb8aa3b, v75
	v_exp_f32_e32 v76, v76
	v_exp_f32_e32 v74, v74
	v_add_f32_e32 v71, 1.0, v71
	v_add_f32_e32 v2, 1.0, v2
	v_add_f32_e32 v76, 1.0, v76
	v_add_f32_e32 v74, 1.0, v74
	v_rcp_f32_e32 v71, v71
	v_rcp_f32_e32 v2, v2
	v_rcp_f32_e32 v81, v76
	v_rcp_f32_e32 v75, v74
	v_lshl_add_u64 v[76:77], v[72:73], 0, v[68:69]
	v_add_co_u32_e32 v76, vcc, s2, v76
	v_cvt_pk_bf16_f32 v72, v71, v78
	v_cvt_pk_bf16_f32 v73, v79, v80
	v_cvt_pk_bf16_f32 v74, v2, v81
	v_cvt_pk_bf16_f32 v75, v82, v75
	v_addc_co_u32_e32 v77, vcc, 0, v77, vcc
	global_store_dwordx4 v[76:77], v[72:75], off offset:768
	s_cbranch_scc1 .LBB0_176
	v_add_u32_e32 v80, 0x80, v70
	v_ashrrev_i32_e32 v81, 31, v80
	v_lshl_add_u64 v[82:83], v[80:81], 2, s[70:71]
	global_load_dword v84, v[82:83], off
	global_load_dword v78, v[82:83], off offset:64
	global_load_dword v74, v[82:83], off offset:128
	global_load_dword v2, v[82:83], off offset:192
	v_lshlrev_b64 v[80:81], 11, v[80:81]
	v_lshl_add_u64 v[80:81], s[94:95], 0, v[80:81]
	v_add_u32_e32 v76, 0x90, v70
	v_ashrrev_i32_e32 v77, 31, v76
	v_lshlrev_b64 v[76:77], 11, v[76:77]
	v_lshl_add_u64 v[76:77], s[94:95], 0, v[76:77]
	v_add_u32_e32 v72, 0xa0, v70
	v_ashrrev_i32_e32 v73, 31, v72
	v_lshlrev_b64 v[72:73], 11, v[72:73]
	v_lshl_add_u64 v[72:73], s[94:95], 0, v[72:73]
	v_add_u32_e32 v70, 0xb0, v70
	v_ashrrev_i32_e32 v71, 31, v70
	v_lshlrev_b64 v[70:71], 11, v[70:71]
	v_lshl_add_u64 v[70:71], s[94:95], 0, v[70:71]
	s_waitcnt vmcnt(0)
	v_pk_mul_f32 v[82:83], v[34:35], v[84:85] op_sel_hi:[1,0]
	s_nop 0
	v_mul_f32_e32 v82, 0xbfb8aa3b, v82
	v_exp_f32_e32 v82, v82
	v_pk_mul_f32 v[86:87], v[32:33], v[84:85] op_sel_hi:[1,0]
	v_add_f32_e32 v82, 1.0, v82
	v_mul_f32_e32 v75, 0xbfb8aa3b, v86
	v_rcp_f32_e32 v86, v82
	v_mul_f32_e32 v82, 0xbfb8aa3b, v83
	v_exp_f32_e32 v82, v82
	v_mul_f32_e32 v79, 0xbfb8aa3b, v87
	v_exp_f32_e32 v75, v75
	v_exp_f32_e32 v79, v79
	v_add_f32_e32 v82, 1.0, v82
	v_rcp_f32_e32 v87, v82
	v_pk_mul_f32 v[82:83], v[30:31], v[84:85] op_sel_hi:[1,0]
	v_pk_mul_f32 v[84:85], v[28:29], v[84:85] op_sel_hi:[1,0]
	v_mul_f32_e32 v82, 0xbfb8aa3b, v82
	v_mul_f32_e32 v84, 0xbfb8aa3b, v84
	v_exp_f32_e32 v84, v84
	v_exp_f32_e32 v82, v82
	v_add_f32_e32 v75, 1.0, v75
	v_add_f32_e32 v79, 1.0, v79
	v_add_f32_e32 v84, 1.0, v84
	v_add_f32_e32 v82, 1.0, v82
	v_rcp_f32_e32 v88, v84
	v_mul_f32_e32 v84, 0xbfb8aa3b, v85
	v_rcp_f32_e32 v90, v82
	v_mul_f32_e32 v82, 0xbfb8aa3b, v83
	v_exp_f32_e32 v84, v84
	v_exp_f32_e32 v82, v82
	v_rcp_f32_e32 v75, v75
	v_rcp_f32_e32 v79, v79
	v_add_f32_e32 v84, 1.0, v84
	v_add_f32_e32 v82, 1.0, v82
	v_rcp_f32_e32 v89, v84
	v_rcp_f32_e32 v83, v82
	v_lshl_add_u64 v[84:85], v[80:81], 0, v[68:69]
	v_add_co_u32_e32 v84, vcc, s2, v84
	v_cvt_pk_bf16_f32 v80, v75, v79
	v_cvt_pk_bf16_f32 v81, v86, v87
	v_cvt_pk_bf16_f32 v82, v88, v89
	v_cvt_pk_bf16_f32 v83, v90, v83
	v_addc_co_u32_e32 v85, vcc, 0, v85, vcc
	global_store_dwordx4 v[84:85], v[80:83], off offset:768
	s_nop 1
	v_pk_mul_f32 v[82:83], v[24:25], v[78:79] op_sel_hi:[1,0]
	v_pk_mul_f32 v[80:81], v[26:27], v[78:79] op_sel_hi:[1,0]
	v_mul_f32_e32 v79, 0xbfb8aa3b, v83
	v_exp_f32_e32 v79, v79
	v_mul_f32_e32 v75, 0xbfb8aa3b, v82
	v_exp_f32_e32 v75, v75
	v_add_f32_e32 v79, 1.0, v79
	v_rcp_f32_e32 v82, v79
	v_mul_f32_e32 v79, 0xbfb8aa3b, v80
	v_exp_f32_e32 v79, v79
	v_add_f32_e32 v75, 1.0, v75
	v_rcp_f32_e32 v75, v75
	v_add_f32_e32 v79, 1.0, v79
	v_rcp_f32_e32 v83, v79
	v_mul_f32_e32 v79, 0xbfb8aa3b, v81
	v_exp_f32_e32 v79, v79
	s_nop 0
	v_add_f32_e32 v79, 1.0, v79
	v_pk_mul_f32 v[80:81], v[22:23], v[78:79] op_sel_hi:[1,0]
	v_rcp_f32_e32 v84, v79
	v_mul_f32_e32 v80, 0xbfb8aa3b, v80
	v_exp_f32_e32 v80, v80
	v_pk_mul_f32 v[78:79], v[20:21], v[78:79] op_sel_hi:[1,0]
	v_add_f32_e32 v80, 1.0, v80
	v_mul_f32_e32 v78, 0xbfb8aa3b, v78
	v_mul_f32_e32 v79, 0xbfb8aa3b, v79
	v_rcp_f32_e32 v85, v80
	v_mul_f32_e32 v80, 0xbfb8aa3b, v81
	v_exp_f32_e32 v78, v78
	v_exp_f32_e32 v79, v79
	v_exp_f32_e32 v80, v80
	v_add_f32_e32 v78, 1.0, v78
	v_add_f32_e32 v79, 1.0, v79
	v_add_f32_e32 v80, 1.0, v80
	v_rcp_f32_e32 v78, v78
	v_rcp_f32_e32 v79, v79
	v_rcp_f32_e32 v86, v80
	v_lshl_add_u64 v[80:81], v[76:77], 0, v[68:69]
	v_add_co_u32_e32 v80, vcc, s2, v80
	v_cvt_pk_bf16_f32 v76, v75, v82
	v_cvt_pk_bf16_f32 v77, v83, v84
	v_cvt_pk_bf16_f32 v78, v78, v79
	v_cvt_pk_bf16_f32 v79, v85, v86
	v_addc_co_u32_e32 v81, vcc, 0, v81, vcc
	global_store_dwordx4 v[80:81], v[76:79], off offset:768
	s_nop 1
	v_pk_mul_f32 v[78:79], v[16:17], v[74:75] op_sel_hi:[1,0]
	v_pk_mul_f32 v[76:77], v[18:19], v[74:75] op_sel_hi:[1,0]
	v_mul_f32_e32 v75, 0xbfb8aa3b, v78
	v_exp_f32_e32 v75, v75
	s_nop 0
	v_add_f32_e32 v75, 1.0, v75
	v_rcp_f32_e32 v78, v75
	v_mul_f32_e32 v75, 0xbfb8aa3b, v79
	v_exp_f32_e32 v75, v75
	s_nop 0
	v_add_f32_e32 v75, 1.0, v75
	v_rcp_f32_e32 v79, v75
	v_mul_f32_e32 v75, 0xbfb8aa3b, v76
	v_exp_f32_e32 v75, v75
	s_nop 0
	v_add_f32_e32 v75, 1.0, v75
	v_rcp_f32_e32 v80, v75
	v_mul_f32_e32 v75, 0xbfb8aa3b, v77
	v_exp_f32_e32 v75, v75
	s_nop 0
	v_add_f32_e32 v75, 1.0, v75
	v_pk_mul_f32 v[76:77], v[14:15], v[74:75] op_sel_hi:[1,0]
	v_rcp_f32_e32 v81, v75
	v_mul_f32_e32 v76, 0xbfb8aa3b, v76
	v_exp_f32_e32 v76, v76
	v_pk_mul_f32 v[74:75], v[12:13], v[74:75] op_sel_hi:[1,0]
	v_add_f32_e32 v76, 1.0, v76
	v_mul_f32_e32 v74, 0xbfb8aa3b, v74
	v_mul_f32_e32 v75, 0xbfb8aa3b, v75
	v_rcp_f32_e32 v82, v76
	v_mul_f32_e32 v76, 0xbfb8aa3b, v77
	v_exp_f32_e32 v74, v74
	v_exp_f32_e32 v75, v75
	v_exp_f32_e32 v76, v76
	v_add_f32_e32 v74, 1.0, v74
	v_add_f32_e32 v75, 1.0, v75
	v_add_f32_e32 v76, 1.0, v76
	v_rcp_f32_e32 v74, v74
	v_rcp_f32_e32 v75, v75
	v_rcp_f32_e32 v83, v76
	v_lshl_add_u64 v[76:77], v[72:73], 0, v[68:69]
	v_add_co_u32_e32 v76, vcc, s2, v76
	v_cvt_pk_bf16_f32 v72, v78, v79
	v_cvt_pk_bf16_f32 v73, v80, v81
	v_cvt_pk_bf16_f32 v74, v74, v75
	v_cvt_pk_bf16_f32 v75, v82, v83
	v_addc_co_u32_e32 v77, vcc, 0, v77, vcc
	global_store_dwordx4 v[76:77], v[72:75], off offset:768
	s_nop 1
	v_pk_mul_f32 v[72:73], v[10:11], v[2:3] op_sel_hi:[1,0]
	v_pk_mul_f32 v[74:75], v[8:9], v[2:3] op_sel_hi:[1,0]
	v_mul_f32_e32 v72, 0xbfb8aa3b, v72
	v_exp_f32_e32 v72, v72
	v_mul_f32_e32 v74, 0xbfb8aa3b, v74
	v_exp_f32_e32 v74, v74
	v_add_f32_e32 v72, 1.0, v72
	v_rcp_f32_e32 v78, v72
	v_mul_f32_e32 v72, 0xbfb8aa3b, v73
	v_exp_f32_e32 v72, v72
	v_add_f32_e32 v74, 1.0, v74
	v_rcp_f32_e32 v76, v74
	v_mul_f32_e32 v74, 0xbfb8aa3b, v75
	v_add_f32_e32 v72, 1.0, v72
	v_rcp_f32_e32 v79, v72
	v_pk_mul_f32 v[72:73], v[6:7], v[2:3] op_sel_hi:[1,0]
	v_exp_f32_e32 v74, v74
	v_mul_f32_e32 v72, 0xbfb8aa3b, v72
	v_exp_f32_e32 v72, v72
	v_add_f32_e32 v74, 1.0, v74
	v_rcp_f32_e32 v77, v74
	v_pk_mul_f32 v[74:75], v[4:5], v[2:3] op_sel_hi:[1,0]
	v_add_f32_e32 v72, 1.0, v72
	v_mul_f32_e32 v2, 0xbfb8aa3b, v74
	v_mul_f32_e32 v74, 0xbfb8aa3b, v75
	v_rcp_f32_e32 v75, v72
	v_mul_f32_e32 v72, 0xbfb8aa3b, v73
	v_exp_f32_e32 v2, v2
	v_exp_f32_e32 v74, v74
	v_exp_f32_e32 v72, v72
	v_add_f32_e32 v2, 1.0, v2
	v_add_f32_e32 v74, 1.0, v74
	v_add_f32_e32 v72, 1.0, v72
	v_rcp_f32_e32 v2, v2
	v_rcp_f32_e32 v74, v74
	v_rcp_f32_e32 v80, v72
	v_lshl_add_u64 v[72:73], v[70:71], 0, v[68:69]
	v_add_co_u32_e32 v72, vcc, s2, v72
	v_cvt_pk_bf16_f32 v68, v76, v77
	v_cvt_pk_bf16_f32 v69, v78, v79
	v_cvt_pk_bf16_f32 v70, v2, v74
	v_cvt_pk_bf16_f32 v71, v75, v80
	v_addc_co_u32_e32 v73, vcc, 0, v73, vcc
	global_store_dwordx4 v[72:73], v[68:71], off offset:768

.LBB0_186:
	s_mov_b64 s[4:5], 0
	s_mov_b64 s[0:1], -1
	s_and_b64 vcc, exec, s[2:3]
	s_cbranch_vccz .LBB0_190
.LBB0_187:
	s_branch .Lsec78_b
.LBB0_189:
	s_mov_b64 s[4:5], 0
